# lora GEMM: K range restricted to the 128-column half that holds the tile's non-zero block of the block-structured weight (2 K-steps instead of 4)
# speedup vs baseline: 1.0077x; 1.0037x over previous
; #define PG8_STAGE(bufoff, gbase, voff) do { _Pragma("unroll") for (int _i = 0; _i < 2; ++_i) \
;         __builtin_amdgcn_global_load_lds((const unsigned*)((const char*)(gbase) + (voff)[_i]), (LAS unsigned*)(lds + (bufoff) + ldsw + _i * 8192), 16, 0, 0); } while (0)
; #define PG8_WAIT_V(n) asm volatile("s_waitcnt vmcnt(" #n ")" ::: "memory")
; #define PG8_BAR __builtin_amdgcn_s_barrier()
;     ...
;     const int tid = tid_, wid = __builtin_amdgcn_readfirstlane(tid >> 6), lane = tid & 63, wr = wid >> 2, wc = wid & 3, fr = lane & 15, fq = lane >> 4;
;     const int K = g.K, nt = K / BK, lda = g.lda, ldb = g.ldb;
;     unsigned voffA[2], voffB[2];
; #pragma unroll
;     for (int i = 0; i < 2; ++i) { int R, C; stage_rc(tid * 16 + i * 8192, R, C); const int Rb = Epi::PERM ? ((R & ~31) + perm32(R & 31)) : R;
;         voffA[i] = (unsigned)(R * lda + C) * 2u; voffB[i] = (unsigned)(Rb * ldb + C) * 2u; }
;     const size_t kstep = (size_t)(BK * 2);
;     const size_t hA = (size_t)HALF * lda * 2, hB = (size_t)HALF * ldb * 2;
;     const size_t tA = 2 * hA, tB = 2 * hB;
;     const unsigned ldsw = (unsigned)wid * 1024u;
;     const int aoff = lds_byte(wr * 64 + fr, fq * 8), boff = lds_byte(wc * 32 + fr, fq * 8);
;     ...
;     Unit cur, nxt; int ui = 0;
;     if (!S.next(0, cur)) return;
;     ...
;     f32x4 acc[2][2][4][2];
; #pragma unroll
;     for (int a = 0; a < 2; ++a)
; #pragma unroll
;         for (int b = 0; b < 2; ++b)
; #pragma unroll
;             for (int m = 0; m < 4; ++m)
; #pragma unroll
;                 for (int n = 0; n < 2; ++n) acc[a][b][m][n] = (f32x4){0.f, 0.f, 0.f, 0.f};
;     bf16x8 At[4][2], B0[2][2], B1[2][2];
;     const char* cA = (const char*)g.A + (size_t)cur.pm * tA; const char* cB = (const char*)g.Bt + (size_t)cur.pn * tB;
;     PG8_A_READY(cur);
;     PG8_STAGE(PG8_SB(0, 0), cB, voffB); PG8_STAGE(PG8_SA(0, 0), cA, voffA); PG8_STAGE(PG8_SB(0, 1), cB + hB, voffB); PG8_STAGE(PG8_SA(0, 1), cA + hA, voffA);
;     if (wr == 1) PG8_BAR;
;     PG8_WAIT_V(4); PG8_BAR;
;     PG8_STAGE(PG8_SB(1, 0), cB + kstep, voffB); PG8_STAGE(PG8_SA(1, 0), cA + kstep, voffA); PG8_STAGE(PG8_SB(1, 1), cB + hB + kstep, voffB);
;     PG8_WAIT_V(6); PG8_BAR;
.LBB0_325:
	s_or_b64 exec, exec, s[8:9]
	s_mov_b32 s53, s2
	s_mov_b32 s51, s46
	s_waitcnt lgkmcnt(0)
	s_barrier
	s_load_dwordx2 s[10:11], s[0:1], 0x138
	s_waitcnt lgkmcnt(0)
	s_load_dwordx2 s[12:13], s[0:1], 0xe8
	s_waitcnt lgkmcnt(0)
	s_load_dwordx2 s[8:9], s[0:1], 0x120
	s_waitcnt lgkmcnt(0)
	s_load_dwordx2 s[14:15], s[0:1], 0x140
	s_waitcnt lgkmcnt(0)
	s_load_dwordx2 s[16:17], s[0:1], 0x148
	s_waitcnt lgkmcnt(0)
	v_mov_b32_e32 v8, v166
	s_cmpk_gt_i32 s53, 0x197
	v_readfirstlane_b32 s70, v8
	s_cbranch_scc1 .LBB0_337
	s_waitcnt vmcnt(2)
	v_lshlrev_b32_e32 v0, 4, v8
	v_add_u32_e32 v1, 0x2000, v0
	v_ashrrev_i32_e32 v2, 31, v1
	v_lshrrev_b32_e32 v2, 22, v2
	v_add_u32_e32 v2, v1, v2
	v_ashrrev_i32_e32 v2, 10, v2
	v_mul_i32_i24_e32 v3, 0x400, v2
	v_sub_u32_e32 v1, v1, v3
	v_lshrrev_b32_e32 v3, 4, v1
	v_bitop3_b32 v1, v3, v1, 32 bitop3:0x6c
	v_ashrrev_i32_e32 v3, 31, v1
	v_lshrrev_b32_e32 v3, 26, v3
	v_add_u32_e32 v3, v1, v3
	s_waitcnt vmcnt(1)
	v_lshlrev_b32_e32 v5, 3, v2
	v_ashrrev_i32_e32 v4, 6, v3
	v_and_b32_e32 v5, -16, v5
	v_and_b32_e32 v3, 0xc0, v3
	v_add_u32_e32 v5, v4, v5
	v_sub_u32_e32 v1, v1, v3
	v_mov_b32_e32 v3, 1
	v_and_b32_e32 v4, 3, v4
	s_mov_b32 s18, 0x7fffe0
	v_lshrrev_b32_e32 v6, 2, v5
	v_lshlrev_b32_e32 v7, 1, v5
	v_lshlrev_b32_e32 v2, 5, v2
	v_ashrrev_i16_sdwa v1, v3, sext(v1) dst_sel:DWORD dst_unused:UNUSED_PAD src0_sel:DWORD src1_sel:BYTE_0
	v_and_or_b32 v4, v5, s18, v4
	v_and_b32_e32 v6, 4, v6
	v_and_b32_e32 v7, 24, v7
	v_and_b32_e32 v2, 32, v2
	v_bfe_i32 v1, v1, 0, 16
	v_or3_b32 v4, v4, v6, v7
	v_add_lshl_u32 v1, v2, v1, 1
	v_lshl_add_u32 v128, v4, 9, v1
	v_lshl_add_u32 v130, v5, 9, v1
	v_bfe_i32 v1, v8, 27, 1
	v_lshrrev_b32_e32 v1, 22, v1
	v_add_u32_e32 v1, v0, v1
	v_and_b32_e32 v1, 0xfffffc00, v1
	v_sub_u32_e32 v0, v0, v1
	v_lshrrev_b32_e32 v1, 4, v0
	v_ashrrev_i32_e32 v4, 31, v8
	v_bitop3_b32 v0, v1, v0, 32 bitop3:0x6c
	v_lshrrev_b32_e32 v4, 26, v4
	v_ashrrev_i32_e32 v1, 31, v0
	v_add_u32_e32 v4, v8, v4
	v_lshrrev_b32_e32 v1, 26, v1
	v_ashrrev_i32_e32 v4, 6, v4
	v_add_u32_e32 v1, v0, v1
	v_lshlrev_b32_e32 v5, 3, v4
	v_ashrrev_i32_e32 v2, 6, v1
	v_and_b32_e32 v5, -16, v5
	v_add_u32_e32 v5, v2, v5
	v_and_b32_e32 v2, 3, v2
	s_ashr_i32 s72, s53, 31
	v_and_or_b32 v2, v5, s18, v2
	s_lshr_b32 s18, s72, 29
	s_add_i32 s18, s53, s18
	s_ashr_i32 s6, s70, 6
	s_ashr_i32 s19, s18, 3
	s_and_b32 s18, s18, -8
	s_ashr_i32 s7, s70, 8
	s_lshl_b32 s71, s6, 10
	s_sub_i32 s18, s53, s18
	s_cmp_lt_i32 s18, 0
	s_cselect_b32 s20, 52, 51
	s_mul_i32 s18, s20, s18
	s_add_i32 s18, s18, s19
	s_mul_hi_i32 s19, s18, 0x2aaaaaab
	v_and_b32_e32 v1, 0xc0, v1
	s_lshr_b32 s20, s19, 31
	s_ashr_i32 s19, s19, 3
	v_sub_u32_e32 v0, v0, v1
	s_add_i32 s19, s19, s20
	v_lshrrev_b32_e32 v6, 2, v5
	v_lshlrev_b32_e32 v7, 1, v5
	v_lshlrev_b32_e32 v4, 5, v4
	v_ashrrev_i16_sdwa v0, v3, sext(v0) dst_sel:DWORD dst_unused:UNUSED_PAD src0_sel:DWORD src1_sel:BYTE_0
	s_lshl_b32 s21, s19, 3
	v_and_b32_e32 v6, 4, v6
	v_and_b32_e32 v7, 24, v7
	v_and_b32_e32 v4, 32, v4
	v_bfe_i32 v0, v0, 0, 16
	s_sub_i32 s20, 0x44, s21
	v_or3_b32 v2, v2, v6, v7
	v_add_lshl_u32 v0, v4, v0, 1
	s_min_u32 s22, s20, 8
	s_mul_i32 s19, s19, 48
	v_lshl_add_u32 v132, v2, 9, v0
	s_sub_i32 s23, s18, s19
	v_cvt_f32_ubyte0_e32 v2, s22
	v_cvt_f32_i32_e32 v1, s23
	v_rcp_iflag_f32_e32 v3, v2
	v_lshl_add_u32 v134, v5, 9, v0
	s_ashr_i32 s18, s23, 30
	s_or_b32 s20, s18, 1
	v_mul_f32_e32 v0, v1, v3
	v_trunc_f32_e32 v0, v0
	v_fma_f32 v1, -v0, v2, v1
	v_cvt_i32_f32_e32 v0, v0
	v_cmp_ge_f32_e64 s[18:19], |v1|, v2
	s_and_b64 s[18:19], s[18:19], exec
	s_cselect_b32 s18, s20, 0
	v_readfirstlane_b32 s19, v0
	s_add_i32 s20, s19, s18
	s_mul_i32 s18, s20, s22
	s_sub_i32 s18, s23, s18
	s_sext_i32_i8 s18, s18
	s_add_i32 s36, s21, s18
	s_ashr_i32 s37, s36, 31
	s_bfe_i64 s[22:23], s[20:21], 0x80000
	s_lshl_b64 s[18:19], s[36:37], 17
	s_lshl_b64 s[22:23], s[22:23], 17
	s_lshr_b32 s98, s22, 19
	s_lshl_b32 s98, s98, 8
	s_add_u32 s22, s22, s98
	s_add_u32 s18, s18, s98
	s_add_u32 s38, s12, s22
	s_addc_u32 s39, s13, s23
	s_add_i32 s37, s71, 0
	s_add_i32 m0, s37, 0x10000
	v_mov_b32_e32 v137, 0
	global_load_lds_dwordx4 v132, s[38:39]
	s_add_i32 m0, s37, 0x12000
	s_add_u32 s40, s10, s18
	global_load_lds_dwordx4 v128, s[38:39]
	s_addc_u32 s41, s11, s19
	s_mov_b32 m0, s37
	s_add_i32 s73, s37, 0x2000
	global_load_lds_dwordx4 v134, s[40:41]
	s_mov_b32 m0, s73
	s_add_u32 s18, s38, 0x10000
	global_load_lds_dwordx4 v130, s[40:41]
	s_addc_u32 s19, s39, 0
	s_add_i32 m0, s37, 0x14000
	v_mov_b32_e32 v133, v137
	global_load_lds_dwordx4 v132, s[18:19]
	s_add_i32 m0, s37, 0x16000
	v_mov_b32_e32 v129, v137
	global_load_lds_dwordx4 v128, s[18:19]
	s_add_u32 s18, s40, 0x10000
	s_addc_u32 s19, s41, 0
	s_add_i32 s74, s37, 0x4000
	s_mov_b32 m0, s74
	s_add_i32 s75, s37, 0x6000
	global_load_lds_dwordx4 v134, s[18:19]
	s_mov_b32 m0, s75
	v_mov_b32_e32 v135, v137
	global_load_lds_dwordx4 v130, s[18:19]
	v_mov_b32_e32 v131, v137
	s_mov_b32 s76, 0
	v_lshl_add_u64 v[6:7], s[38:39], 0, v[132:133]
	v_lshl_add_u64 v[4:5], s[38:39], 0, v[128:129]
	v_lshl_add_u64 v[2:3], s[40:41], 0, v[134:135]
	s_cmp_lg_u32 s7, 1
	v_lshl_add_u64 v[0:1], s[40:41], 0, v[130:131]
	s_cbranch_scc1 .LBB0_328
	s_barrier

; #define PG8_WAIT_V(n) asm volatile("s_waitcnt vmcnt(" #n ")" ::: "memory")
;     ...
;         const bool has_next = S.next(ui + 1, nxt);
;         const char* nA = has_next ? (const char*)g.A + (size_t)nxt.pm * tA : cA; const char* nB = has_next ? (const char*)g.Bt + (size_t)nxt.pn * tB : cB;
; #pragma unroll 1
;         for (int t = 0; t < nt; t += 2) {
;             const bool last = (t == nt - 2);
;             const char* a1 = cA + (size_t)(t + 1) * kstep;
;             const char* a2 = last ? nA : cA + (size_t)(t + 2) * kstep; const char* b2 = last ? nB : cB + (size_t)(t + 2) * kstep;
;             const char* a3 = a2 + kstep; const char* b3 = b2 + kstep;
;             if (last && has_next) PG8_A_READY(nxt);
;             PG8_LDB(B0, 0, 0); PG8_SCHED; PG8_LDA(At, 0, 0); PG8_STAGE(PG8_SA(1, 1), a1 + hA, voffA);
;             PG8_WAIT_L(8); PG8_BAR; PG8_WAIT_L(0); PG8_MMA(0, 0, At, B0); PG8_BAR; PG8_SCHED;
;             PG8_LDB(B1, 0, 1); PG8_STAGE(PG8_SB(0, 0), b2, voffB);
;             PG8_BAR; PG8_WAIT_L(0); PG8_MMA(0, 1, At, B1); PG8_BAR;
;             PG8_LDA(At, 0, 1); PG8_STAGE(PG8_SA(0, 0), a2, voffA);
;             PG8_BAR; PG8_WAIT_L(0); PG8_MMA(1, 0, At, B0); PG8_BAR; PG8_SCHED;
;             PG8_STAGE(PG8_SB(0, 1), b2 + hB, voffB);
;             PG8_WAIT_V(6); PG8_BAR; PG8_MMA(1, 1, At, B1); PG8_BAR;
;             PG8_LDB(B0, 1, 0); PG8_SCHED; PG8_LDA(At, 1, 0); PG8_STAGE(PG8_SA(0, 1), a2 + hA, voffA);
;             PG8_WAIT_L(8); PG8_BAR; PG8_WAIT_L(0); PG8_MMA(0, 0, At, B0); PG8_BAR; PG8_SCHED;
;             PG8_LDB(B1, 1, 1); PG8_STAGE(PG8_SB(1, 0), b3, voffB);
;             PG8_BAR; PG8_WAIT_L(0); PG8_MMA(0, 1, At, B1); PG8_BAR;
;             PG8_LDA(At, 1, 1); PG8_STAGE(PG8_SA(1, 0), a3, voffA);
;             PG8_BAR; PG8_WAIT_L(0); PG8_MMA(1, 0, At, B0); PG8_BAR; PG8_SCHED;
;             PG8_STAGE(PG8_SB(1, 1), b3 + hB, voffB);
;             PG8_WAIT_V(6); PG8_BAR; PG8_MMA(1, 1, At, B1); PG8_BAR;
;         }
;         E(acc, cur, wr, wc, fr, fq);
;         if (!has_next) break;
; #pragma unroll
;         for (int a = 0; a < 2; ++a)
; #pragma unroll
;             for (int b = 0; b < 2; ++b)
; #pragma unroll
;                 for (int m = 0; m < 4; ++m)
; #pragma unroll
;                     for (int n = 0; n < 2; ++n) acc[a][b][m][n] = (f32x4){0.f, 0.f, 0.f, 0.f};
;         cur = nxt; cA = nA; cB = nB; ++ui;
.LBB0_331:
	s_ashr_i32 s29, s28, 31
	v_cmp_lt_i64_e32 vcc, s[30:31], v[138:139]
	s_lshl_b64 s[30:31], s[28:29], 17
	s_lshr_b32 s98, s26, 2
	s_lshl_b32 s98, s98, 8
	s_add_u32 s30, s30, s98
	s_add_u32 s30, s10, s30
	s_addc_u32 s31, s11, s31
	s_and_b64 s[34:35], vcc, exec
	s_cselect_b32 s7, s31, s41
	s_cselect_b32 s29, s30, s40
	s_ashr_i32 s27, s26, 31
	s_lshl_b64 s[34:35], s[26:27], 17
	s_add_u32 s34, s34, s98
	s_add_u32 s34, s12, s34
	s_addc_u32 s35, s13, s35
	s_and_b64 s[42:43], vcc, exec
	v_mov_b32_e32 v0, 0
	s_cselect_b32 s27, s35, s39
	s_cselect_b32 s42, s34, s38
	s_mov_b64 s[60:61], 0
	s_mov_b64 s[56:57], 0
	s_mov_b64 s[58:59], -1
	v_mov_b32_e32 v1, v0
	v_mov_b32_e32 v2, v0
	v_mov_b32_e32 v3, v0
	v_mov_b32_e32 v4, v0
	v_mov_b32_e32 v5, v0
	v_mov_b32_e32 v6, v0
	v_mov_b32_e32 v7, v0
	v_mov_b32_e32 v8, v0
	v_mov_b32_e32 v9, v0
	v_mov_b32_e32 v10, v0
	v_mov_b32_e32 v11, v0
	v_mov_b32_e32 v16, v0
	v_mov_b32_e32 v17, v0
	v_mov_b32_e32 v18, v0
	v_mov_b32_e32 v19, v0
	v_mov_b32_e32 v24, v0
	v_mov_b32_e32 v25, v0
	v_mov_b32_e32 v26, v0
	v_mov_b32_e32 v27, v0
	v_mov_b32_e32 v32, v0
	v_mov_b32_e32 v33, v0
	v_mov_b32_e32 v34, v0
	v_mov_b32_e32 v35, v0
	v_mov_b32_e32 v40, v0
	v_mov_b32_e32 v41, v0
	v_mov_b32_e32 v42, v0
	v_mov_b32_e32 v43, v0
	v_mov_b32_e32 v48, v0
	v_mov_b32_e32 v49, v0
	v_mov_b32_e32 v50, v0
	v_mov_b32_e32 v51, v0
	v_mov_b32_e32 v12, v0
	v_mov_b32_e32 v13, v0
	v_mov_b32_e32 v14, v0
	v_mov_b32_e32 v15, v0
	v_mov_b32_e32 v20, v0
	v_mov_b32_e32 v21, v0
	v_mov_b32_e32 v22, v0
	v_mov_b32_e32 v23, v0
	v_mov_b32_e32 v28, v0
	v_mov_b32_e32 v29, v0
	v_mov_b32_e32 v30, v0
	v_mov_b32_e32 v31, v0
	v_mov_b32_e32 v36, v0
	v_mov_b32_e32 v37, v0
	v_mov_b32_e32 v38, v0
	v_mov_b32_e32 v39, v0
	v_mov_b32_e32 v44, v0
	v_mov_b32_e32 v45, v0
	v_mov_b32_e32 v46, v0
	v_mov_b32_e32 v47, v0
	v_mov_b32_e32 v52, v0
	v_mov_b32_e32 v53, v0
	v_mov_b32_e32 v54, v0
	v_mov_b32_e32 v55, v0
	v_mov_b32_e32 v56, v0
	v_mov_b32_e32 v57, v0
	v_mov_b32_e32 v58, v0
	v_mov_b32_e32 v59, v0
	v_mov_b32_e32 v60, v0
	v_mov_b32_e32 v61, v0
	v_mov_b32_e32 v62, v0
	v_mov_b32_e32 v63, v0
	v_mov_b32_e32 v64, v0
	v_mov_b32_e32 v65, v0
	v_mov_b32_e32 v66, v0
	v_mov_b32_e32 v67, v0
	v_mov_b32_e32 v68, v0
	v_mov_b32_e32 v69, v0
	v_mov_b32_e32 v70, v0
	v_mov_b32_e32 v71, v0
	v_mov_b32_e32 v72, v0
	v_mov_b32_e32 v73, v0
	v_mov_b32_e32 v74, v0
	v_mov_b32_e32 v75, v0
	v_mov_b32_e32 v80, v0
	v_mov_b32_e32 v81, v0
	v_mov_b32_e32 v82, v0
	v_mov_b32_e32 v83, v0
	v_mov_b32_e32 v88, v0
	v_mov_b32_e32 v89, v0
	v_mov_b32_e32 v90, v0
	v_mov_b32_e32 v91, v0
	v_mov_b32_e32 v96, v0
	v_mov_b32_e32 v97, v0
	v_mov_b32_e32 v98, v0
	v_mov_b32_e32 v99, v0
	v_mov_b32_e32 v104, v0
	v_mov_b32_e32 v105, v0
	v_mov_b32_e32 v106, v0
	v_mov_b32_e32 v107, v0
	v_mov_b32_e32 v112, v0
	v_mov_b32_e32 v113, v0
	v_mov_b32_e32 v114, v0
	v_mov_b32_e32 v115, v0
	v_mov_b32_e32 v76, v0
	v_mov_b32_e32 v77, v0
	v_mov_b32_e32 v78, v0
	v_mov_b32_e32 v79, v0
	v_mov_b32_e32 v84, v0
	v_mov_b32_e32 v85, v0
	v_mov_b32_e32 v86, v0
	v_mov_b32_e32 v87, v0
	v_mov_b32_e32 v92, v0
	v_mov_b32_e32 v93, v0
	v_mov_b32_e32 v94, v0
	v_mov_b32_e32 v95, v0
	v_mov_b32_e32 v100, v0
	v_mov_b32_e32 v101, v0
	v_mov_b32_e32 v102, v0
	v_mov_b32_e32 v103, v0
	v_mov_b32_e32 v108, v0
	v_mov_b32_e32 v109, v0
	v_mov_b32_e32 v110, v0
	v_mov_b32_e32 v111, v0
	v_mov_b32_e32 v116, v0
	v_mov_b32_e32 v117, v0
	v_mov_b32_e32 v118, v0
	v_mov_b32_e32 v119, v0
	v_mov_b32_e32 v120, v0
	v_mov_b32_e32 v121, v0
	v_mov_b32_e32 v122, v0
	v_mov_b32_e32 v123, v0
	v_mov_b32_e32 v124, v0
	v_mov_b32_e32 v125, v0
	v_mov_b32_e32 v126, v0
	v_mov_b32_e32 v127, v0

; #define PG8_STAGE(bufoff, gbase, voff) do { _Pragma("unroll") for (int _i = 0; _i < 2; ++_i) \
;         __builtin_amdgcn_global_load_lds((const unsigned*)((const char*)(gbase) + (voff)[_i]), (LAS unsigned*)(lds + (bufoff) + ldsw + _i * 8192), 16, 0, 0); } while (0)
; #define PG8_WAIT_V(n) asm volatile("s_waitcnt vmcnt(" #n ")" ::: "memory")
; #define PG8_BAR __builtin_amdgcn_s_barrier()
;     ...
;     const int tid = tid_, wid = __builtin_amdgcn_readfirstlane(tid >> 6), lane = tid & 63, wr = wid >> 2, wc = wid & 3, fr = lane & 15, fq = lane >> 4;
;     const int K = g.K, nt = K / BK, lda = g.lda, ldb = g.ldb;
;     unsigned voffA[2], voffB[2];
; #pragma unroll
;     for (int i = 0; i < 2; ++i) { int R, C; stage_rc(tid * 16 + i * 8192, R, C); const int Rb = Epi::PERM ? ((R & ~31) + perm32(R & 31)) : R;
;         voffA[i] = (unsigned)(R * lda + C) * 2u; voffB[i] = (unsigned)(Rb * ldb + C) * 2u; }
;     const size_t kstep = (size_t)(BK * 2);
;     const size_t hA = (size_t)HALF * lda * 2, hB = (size_t)HALF * ldb * 2;
;     const size_t tA = 2 * hA, tB = 2 * hB;
;     const unsigned ldsw = (unsigned)wid * 1024u;
;     const int aoff = lds_byte(wr * 64 + fr, fq * 8), boff = lds_byte(wc * 32 + fr, fq * 8);
;     ...
;     Unit cur, nxt; int ui = 0;
;     if (!S.next(0, cur)) return;
;     ...
;     f32x4 acc[2][2][4][2];
; #pragma unroll
;     for (int a = 0; a < 2; ++a)
; #pragma unroll
;         for (int b = 0; b < 2; ++b)
; #pragma unroll
;             for (int m = 0; m < 4; ++m)
; #pragma unroll
;                 for (int n = 0; n < 2; ++n) acc[a][b][m][n] = (f32x4){0.f, 0.f, 0.f, 0.f};
;     bf16x8 At[4][2], B0[2][2], B1[2][2];
;     const char* cA = (const char*)g.A + (size_t)cur.pm * tA; const char* cB = (const char*)g.Bt + (size_t)cur.pn * tB;
;     PG8_A_READY(cur);
;     PG8_STAGE(PG8_SB(0, 0), cB, voffB); PG8_STAGE(PG8_SA(0, 0), cA, voffA); PG8_STAGE(PG8_SB(0, 1), cB + hB, voffB); PG8_STAGE(PG8_SA(0, 1), cA + hA, voffA);
;     if (wr == 1) PG8_BAR;
;     PG8_WAIT_V(4); PG8_BAR;
;     PG8_STAGE(PG8_SB(1, 0), cB + kstep, voffB); PG8_STAGE(PG8_SA(1, 0), cA + kstep, voffA); PG8_STAGE(PG8_SB(1, 1), cB + hB + kstep, voffB);
;     PG8_WAIT_V(6); PG8_BAR;
.LBB0_1466:
	s_or_b64 exec, exec, s[10:11]
	s_mov_b32 s53, s46
	s_mov_b32 s68, s2
	s_waitcnt lgkmcnt(0)
	s_barrier
	s_load_dwordx2 s[12:13], s[0:1], 0x138
	s_waitcnt lgkmcnt(0)
	s_load_dwordx2 s[14:15], s[0:1], 0xe8
	s_waitcnt lgkmcnt(0)
	s_load_dwordx2 s[10:11], s[0:1], 0x120
	s_waitcnt lgkmcnt(0)
	s_load_dwordx2 s[16:17], s[0:1], 0x140
	s_waitcnt lgkmcnt(0)
	s_load_dwordx2 s[18:19], s[0:1], 0x148
	s_waitcnt lgkmcnt(0)
	v_mov_b32_e32 v8, v166
	s_cmpk_gt_i32 s68, 0x197
	v_readfirstlane_b32 s69, v8
	s_cbranch_scc1 .LBB0_1478
	s_waitcnt vmcnt(2)
	v_lshlrev_b32_e32 v0, 4, v8
	v_add_u32_e32 v1, 0x2000, v0
	v_ashrrev_i32_e32 v2, 31, v1
	v_lshrrev_b32_e32 v2, 22, v2
	v_add_u32_e32 v2, v1, v2
	v_ashrrev_i32_e32 v2, 10, v2
	v_mul_i32_i24_e32 v3, 0x400, v2
	v_sub_u32_e32 v1, v1, v3
	v_lshrrev_b32_e32 v3, 4, v1
	v_bitop3_b32 v1, v3, v1, 32 bitop3:0x6c
	v_ashrrev_i32_e32 v3, 31, v1
	v_lshrrev_b32_e32 v3, 26, v3
	v_add_u32_e32 v3, v1, v3
	s_waitcnt vmcnt(1)
	v_lshlrev_b32_e32 v5, 3, v2
	v_ashrrev_i32_e32 v4, 6, v3
	v_and_b32_e32 v5, -16, v5
	v_and_b32_e32 v3, 0xc0, v3
	v_add_u32_e32 v5, v4, v5
	v_sub_u32_e32 v1, v1, v3
	v_mov_b32_e32 v3, 1
	v_and_b32_e32 v4, 3, v4
	s_mov_b32 s8, 0x7fffe0
	v_lshrrev_b32_e32 v6, 2, v5
	v_lshlrev_b32_e32 v7, 1, v5
	v_lshlrev_b32_e32 v2, 5, v2
	v_ashrrev_i16_sdwa v1, v3, sext(v1) dst_sel:DWORD dst_unused:UNUSED_PAD src0_sel:DWORD src1_sel:BYTE_0
	v_and_or_b32 v4, v5, s8, v4
	v_and_b32_e32 v6, 4, v6
	v_and_b32_e32 v7, 24, v7
	v_and_b32_e32 v2, 32, v2
	v_bfe_i32 v1, v1, 0, 16
	v_or3_b32 v4, v4, v6, v7
	v_add_lshl_u32 v1, v2, v1, 1
	v_lshl_add_u32 v128, v4, 9, v1
	v_lshl_add_u32 v130, v5, 9, v1
	v_bfe_i32 v1, v8, 27, 1
	v_lshrrev_b32_e32 v1, 22, v1
	v_add_u32_e32 v1, v0, v1
	v_and_b32_e32 v1, 0xfffffc00, v1
	v_sub_u32_e32 v0, v0, v1
	v_lshrrev_b32_e32 v1, 4, v0
	v_ashrrev_i32_e32 v4, 31, v8
	v_bitop3_b32 v0, v1, v0, 32 bitop3:0x6c
	v_lshrrev_b32_e32 v4, 26, v4
	v_ashrrev_i32_e32 v1, 31, v0
	v_add_u32_e32 v4, v8, v4
	v_lshrrev_b32_e32 v1, 26, v1
	v_ashrrev_i32_e32 v4, 6, v4
	v_add_u32_e32 v1, v0, v1
	v_lshlrev_b32_e32 v5, 3, v4
	v_ashrrev_i32_e32 v2, 6, v1
	v_and_b32_e32 v5, -16, v5
	v_add_u32_e32 v5, v2, v5
	v_and_b32_e32 v2, 3, v2
	s_ashr_i32 s71, s68, 31
	v_and_or_b32 v2, v5, s8, v2
	s_lshr_b32 s8, s71, 29
	s_add_i32 s8, s68, s8
	s_ashr_i32 s6, s69, 6
	s_ashr_i32 s9, s8, 3
	s_and_b32 s8, s8, -8
	s_ashr_i32 s7, s69, 8
	s_lshl_b32 s70, s6, 10
	s_sub_i32 s8, s68, s8
	s_cmp_lt_i32 s8, 0
	s_cselect_b32 s20, 52, 51
	s_mul_i32 s8, s20, s8
	s_add_i32 s8, s8, s9
	s_mul_hi_i32 s9, s8, 0x2aaaaaab
	v_and_b32_e32 v1, 0xc0, v1
	s_lshr_b32 s20, s9, 31
	s_ashr_i32 s9, s9, 3
	v_sub_u32_e32 v0, v0, v1
	s_add_i32 s9, s9, s20
	v_lshrrev_b32_e32 v6, 2, v5
	v_lshlrev_b32_e32 v7, 1, v5
	v_lshlrev_b32_e32 v4, 5, v4
	v_ashrrev_i16_sdwa v0, v3, sext(v0) dst_sel:DWORD dst_unused:UNUSED_PAD src0_sel:DWORD src1_sel:BYTE_0
	s_lshl_b32 s20, s9, 3
	v_and_b32_e32 v6, 4, v6
	v_and_b32_e32 v7, 24, v7
	v_and_b32_e32 v4, 32, v4
	v_bfe_i32 v0, v0, 0, 16
	s_sub_i32 s21, 0x44, s20
	v_or3_b32 v2, v2, v6, v7
	v_add_lshl_u32 v0, v4, v0, 1
	s_min_u32 s21, s21, 8
	s_mul_i32 s9, s9, 48
	v_lshl_add_u32 v132, v2, 9, v0
	s_sub_i32 s23, s8, s9
	v_cvt_f32_ubyte0_e32 v2, s21
	v_cvt_f32_i32_e32 v1, s23
	v_rcp_iflag_f32_e32 v3, v2
	v_lshl_add_u32 v134, v5, 9, v0
	s_ashr_i32 s8, s23, 30
	s_or_b32 s22, s8, 1
	v_mul_f32_e32 v0, v1, v3
	v_trunc_f32_e32 v0, v0
	v_fma_f32 v1, -v0, v2, v1
	v_cvt_i32_f32_e32 v0, v0
	v_cmp_ge_f32_e64 s[8:9], |v1|, v2
	s_and_b64 s[8:9], s[8:9], exec
	s_cselect_b32 s8, s22, 0
	v_readfirstlane_b32 s9, v0
	s_add_i32 s22, s9, s8
	s_mul_i32 s8, s22, s21
	s_sub_i32 s8, s23, s8
	s_sext_i32_i8 s8, s8
	s_add_i32 s38, s20, s8
	s_ashr_i32 s39, s38, 31
	s_bfe_i64 s[20:21], s[22:23], 0x80000
	s_lshl_b64 s[8:9], s[38:39], 17
	s_lshl_b64 s[20:21], s[20:21], 17
	s_lshr_b32 s98, s20, 19
	s_lshl_b32 s98, s98, 8
	s_add_u32 s20, s20, s98
	s_add_u32 s8, s8, s98
	s_add_u32 s40, s14, s20
	s_addc_u32 s41, s15, s21
	s_add_i32 s39, s70, 0
	s_add_i32 m0, s39, 0x10000
	v_mov_b32_e32 v137, 0
	global_load_lds_dwordx4 v132, s[40:41]
	s_add_i32 m0, s39, 0x12000
	s_add_u32 s42, s12, s8
	global_load_lds_dwordx4 v128, s[40:41]
	s_addc_u32 s43, s13, s9
	s_mov_b32 m0, s39
	s_add_i32 s72, s39, 0x2000
	global_load_lds_dwordx4 v134, s[42:43]
	s_mov_b32 m0, s72
	s_add_u32 s8, s40, 0x10000
	global_load_lds_dwordx4 v130, s[42:43]
	s_addc_u32 s9, s41, 0
	s_add_i32 m0, s39, 0x14000
	v_mov_b32_e32 v133, v137
	global_load_lds_dwordx4 v132, s[8:9]
	s_add_i32 m0, s39, 0x16000
	v_mov_b32_e32 v129, v137
	global_load_lds_dwordx4 v128, s[8:9]
	s_add_u32 s8, s42, 0x10000
	s_addc_u32 s9, s43, 0
	s_add_i32 s73, s39, 0x4000
	s_mov_b32 m0, s73
	s_add_i32 s74, s39, 0x6000
	global_load_lds_dwordx4 v134, s[8:9]
	s_mov_b32 m0, s74
	v_mov_b32_e32 v135, v137
	global_load_lds_dwordx4 v130, s[8:9]
	v_mov_b32_e32 v131, v137
	s_mov_b32 s75, 0
	v_lshl_add_u64 v[6:7], s[40:41], 0, v[132:133]
	v_lshl_add_u64 v[4:5], s[40:41], 0, v[128:129]
	v_lshl_add_u64 v[2:3], s[42:43], 0, v[134:135]
	s_cmp_lg_u32 s7, 1
	v_lshl_add_u64 v[0:1], s[42:43], 0, v[130:131]
	s_cbranch_scc1 .LBB0_1469
	s_barrier

; #define PG8_WAIT_V(n) asm volatile("s_waitcnt vmcnt(" #n ")" ::: "memory")
;     ...
;         const bool has_next = S.next(ui + 1, nxt);
;         const char* nA = has_next ? (const char*)g.A + (size_t)nxt.pm * tA : cA; const char* nB = has_next ? (const char*)g.Bt + (size_t)nxt.pn * tB : cB;
; #pragma unroll 1
;         for (int t = 0; t < nt; t += 2) {
;             const bool last = (t == nt - 2);
;             const char* a1 = cA + (size_t)(t + 1) * kstep;
;             const char* a2 = last ? nA : cA + (size_t)(t + 2) * kstep; const char* b2 = last ? nB : cB + (size_t)(t + 2) * kstep;
;             const char* a3 = a2 + kstep; const char* b3 = b2 + kstep;
;             if (last && has_next) PG8_A_READY(nxt);
;             PG8_LDB(B0, 0, 0); PG8_SCHED; PG8_LDA(At, 0, 0); PG8_STAGE(PG8_SA(1, 1), a1 + hA, voffA);
;             PG8_WAIT_L(8); PG8_BAR; PG8_WAIT_L(0); PG8_MMA(0, 0, At, B0); PG8_BAR; PG8_SCHED;
;             PG8_LDB(B1, 0, 1); PG8_STAGE(PG8_SB(0, 0), b2, voffB);
;             PG8_BAR; PG8_WAIT_L(0); PG8_MMA(0, 1, At, B1); PG8_BAR;
;             PG8_LDA(At, 0, 1); PG8_STAGE(PG8_SA(0, 0), a2, voffA);
;             PG8_BAR; PG8_WAIT_L(0); PG8_MMA(1, 0, At, B0); PG8_BAR; PG8_SCHED;
;             PG8_STAGE(PG8_SB(0, 1), b2 + hB, voffB);
;             PG8_WAIT_V(6); PG8_BAR; PG8_MMA(1, 1, At, B1); PG8_BAR;
;             PG8_LDB(B0, 1, 0); PG8_SCHED; PG8_LDA(At, 1, 0); PG8_STAGE(PG8_SA(0, 1), a2 + hA, voffA);
;             PG8_WAIT_L(8); PG8_BAR; PG8_WAIT_L(0); PG8_MMA(0, 0, At, B0); PG8_BAR; PG8_SCHED;
;             PG8_LDB(B1, 1, 1); PG8_STAGE(PG8_SB(1, 0), b3, voffB);
;             PG8_BAR; PG8_WAIT_L(0); PG8_MMA(0, 1, At, B1); PG8_BAR;
;             PG8_LDA(At, 1, 1); PG8_STAGE(PG8_SA(1, 0), a3, voffA);
;             PG8_BAR; PG8_WAIT_L(0); PG8_MMA(1, 0, At, B0); PG8_BAR; PG8_SCHED;
;             PG8_STAGE(PG8_SB(1, 1), b3 + hB, voffB);
;             PG8_WAIT_V(6); PG8_BAR; PG8_MMA(1, 1, At, B1); PG8_BAR;
;         }
;         E(acc, cur, wr, wc, fr, fq);
;         if (!has_next) break;
; #pragma unroll
;         for (int a = 0; a < 2; ++a)
; #pragma unroll
;             for (int b = 0; b < 2; ++b)
; #pragma unroll
;                 for (int m = 0; m < 4; ++m)
; #pragma unroll
;                     for (int n = 0; n < 2; ++n) acc[a][b][m][n] = (f32x4){0.f, 0.f, 0.f, 0.f};
;         cur = nxt; cA = nA; cB = nB; ++ui;
.LBB0_1472:
	s_ashr_i32 s31, s30, 31
	s_lshl_b64 s[8:9], s[30:31], 17
	s_lshr_b32 s98, s28, 2
	s_lshl_b32 s98, s98, 8
	s_add_u32 s8, s8, s98
	v_cmp_lt_i64_e32 vcc, s[34:35], v[138:139]
	s_add_u32 s34, s12, s8
	s_addc_u32 s35, s13, s9
	s_and_b64 s[8:9], vcc, exec
	s_cselect_b32 s7, s35, s43
	s_cselect_b32 s8, s34, s42
	s_ashr_i32 s29, s28, 31
	s_lshl_b64 s[36:37], s[28:29], 17
	s_add_u32 s36, s36, s98
	s_add_u32 s36, s14, s36
	s_addc_u32 s37, s15, s37
	s_and_b64 s[44:45], vcc, exec
	v_mov_b32_e32 v0, 0
	s_cselect_b32 s9, s37, s41
	s_cselect_b32 s29, s36, s40
	s_mov_b64 s[58:59], 0
	s_mov_b64 s[54:55], 0
	s_mov_b64 s[56:57], -1
	v_mov_b32_e32 v1, v0
	v_mov_b32_e32 v2, v0
	v_mov_b32_e32 v3, v0
	v_mov_b32_e32 v4, v0
	v_mov_b32_e32 v5, v0
	v_mov_b32_e32 v6, v0
	v_mov_b32_e32 v7, v0
	v_mov_b32_e32 v8, v0
	v_mov_b32_e32 v9, v0
	v_mov_b32_e32 v10, v0
	v_mov_b32_e32 v11, v0
	v_mov_b32_e32 v16, v0
	v_mov_b32_e32 v17, v0
	v_mov_b32_e32 v18, v0
	v_mov_b32_e32 v19, v0
	v_mov_b32_e32 v24, v0
	v_mov_b32_e32 v25, v0
	v_mov_b32_e32 v26, v0
	v_mov_b32_e32 v27, v0
	v_mov_b32_e32 v32, v0
	v_mov_b32_e32 v33, v0
	v_mov_b32_e32 v34, v0
	v_mov_b32_e32 v35, v0
	v_mov_b32_e32 v40, v0
	v_mov_b32_e32 v41, v0
	v_mov_b32_e32 v42, v0
	v_mov_b32_e32 v43, v0
	v_mov_b32_e32 v48, v0
	v_mov_b32_e32 v49, v0
	v_mov_b32_e32 v50, v0
	v_mov_b32_e32 v51, v0
	v_mov_b32_e32 v12, v0
	v_mov_b32_e32 v13, v0
	v_mov_b32_e32 v14, v0
	v_mov_b32_e32 v15, v0
	v_mov_b32_e32 v20, v0
	v_mov_b32_e32 v21, v0
	v_mov_b32_e32 v22, v0
	v_mov_b32_e32 v23, v0
	v_mov_b32_e32 v28, v0
	v_mov_b32_e32 v29, v0
	v_mov_b32_e32 v30, v0
	v_mov_b32_e32 v31, v0
	v_mov_b32_e32 v36, v0
	v_mov_b32_e32 v37, v0
	v_mov_b32_e32 v38, v0
	v_mov_b32_e32 v39, v0
	v_mov_b32_e32 v44, v0
	v_mov_b32_e32 v45, v0
	v_mov_b32_e32 v46, v0
	v_mov_b32_e32 v47, v0
	v_mov_b32_e32 v52, v0
	v_mov_b32_e32 v53, v0
	v_mov_b32_e32 v54, v0
	v_mov_b32_e32 v55, v0
	v_mov_b32_e32 v56, v0
	v_mov_b32_e32 v57, v0
	v_mov_b32_e32 v58, v0
	v_mov_b32_e32 v59, v0
	v_mov_b32_e32 v60, v0
	v_mov_b32_e32 v61, v0
	v_mov_b32_e32 v62, v0
	v_mov_b32_e32 v63, v0
	v_mov_b32_e32 v64, v0
	v_mov_b32_e32 v65, v0
	v_mov_b32_e32 v66, v0
	v_mov_b32_e32 v67, v0
	v_mov_b32_e32 v68, v0
	v_mov_b32_e32 v69, v0
	v_mov_b32_e32 v70, v0
	v_mov_b32_e32 v71, v0
	v_mov_b32_e32 v72, v0
	v_mov_b32_e32 v73, v0
	v_mov_b32_e32 v74, v0
	v_mov_b32_e32 v75, v0
	v_mov_b32_e32 v80, v0
	v_mov_b32_e32 v81, v0
	v_mov_b32_e32 v82, v0
	v_mov_b32_e32 v83, v0
	v_mov_b32_e32 v88, v0
	v_mov_b32_e32 v89, v0
	v_mov_b32_e32 v90, v0
	v_mov_b32_e32 v91, v0
	v_mov_b32_e32 v96, v0
	v_mov_b32_e32 v97, v0
	v_mov_b32_e32 v98, v0
	v_mov_b32_e32 v99, v0
	v_mov_b32_e32 v104, v0
	v_mov_b32_e32 v105, v0
	v_mov_b32_e32 v106, v0
	v_mov_b32_e32 v107, v0
	v_mov_b32_e32 v112, v0
	v_mov_b32_e32 v113, v0
	v_mov_b32_e32 v114, v0
	v_mov_b32_e32 v115, v0
	v_mov_b32_e32 v76, v0
	v_mov_b32_e32 v77, v0
	v_mov_b32_e32 v78, v0
	v_mov_b32_e32 v79, v0
	v_mov_b32_e32 v84, v0
	v_mov_b32_e32 v85, v0
	v_mov_b32_e32 v86, v0
	v_mov_b32_e32 v87, v0
	v_mov_b32_e32 v92, v0
	v_mov_b32_e32 v93, v0
	v_mov_b32_e32 v94, v0
	v_mov_b32_e32 v95, v0
	v_mov_b32_e32 v100, v0
	v_mov_b32_e32 v101, v0
	v_mov_b32_e32 v102, v0
	v_mov_b32_e32 v103, v0
	v_mov_b32_e32 v108, v0
	v_mov_b32_e32 v109, v0
	v_mov_b32_e32 v110, v0
	v_mov_b32_e32 v111, v0
	v_mov_b32_e32 v116, v0
	v_mov_b32_e32 v117, v0
	v_mov_b32_e32 v118, v0
	v_mov_b32_e32 v119, v0
	v_mov_b32_e32 v120, v0
	v_mov_b32_e32 v121, v0
	v_mov_b32_e32 v122, v0
	v_mov_b32_e32 v123, v0
	v_mov_b32_e32 v124, v0
	v_mov_b32_e32 v125, v0
	v_mov_b32_e32 v126, v0
	v_mov_b32_e32 v127, v0
